# MLA up-projection (kv) epilogue: hoist the 8 row-scale dwordx4 loads above the bf16 stores into free VGPRs, counted vmcnt (no more vmcnt(0) stalls on stores)
# speedup vs baseline: 1.0042x; 1.0042x over previous
; __device__ __forceinline__ uint32_t pk2(float lo, float hi) { typedef float f2 __attribute__((ext_vector_type(2))); const f2 v = {lo, hi}; return __builtin_bit_cast(uint32_t, __builtin_convertvector(v, bf16x2_t)); }
; __device__ __forceinline__ void mla_up_tile(const Params& p, int b, int it, unsigned char* lds) {
;     ...
;         const int j = it - 384, pn = j & 3, pm = j >> 2;
;         gemm_big(PB + (size_t)pm * 128 * PBW + PB_CKV, PBW, wb + W_UKV + (size_t)pn * 256 * 128, 128, acc, lds);
;         const float* RKV = (const float*)(p.ws + OFF_RKV);
;         bf16_t* KM = (bf16_t*)(p.ws + OFF_KM); bf16_t* VTM = (bf16_t*)(p.ws + OFF_VTM);
;         const int head = pn * 2 + wc;
; #pragma unroll
;         for (int mi = 0; mi < 2; ++mi) {
;             const int mb = pm * 128 + wr * 64 + mi * 32 + 4 * h;
;             float rs[16];
; #pragma unroll
;             for (int reg = 0; reg < 16; ++reg) rs[reg] = RKV[mb + (reg & 3) + 8 * (reg >> 2)];
; #pragma unroll
;             for (int ni = 0; ni < 2; ++ni) {
; #pragma unroll
;                 for (int reg = 0; reg < 16; ++reg)
;                     KM[((size_t)(mb + (reg & 3) + 8 * (reg >> 2)) * 8 + head) * 96 + ni * 32 + r] = (bf16_t)(pk2(acc[mi][ni][reg] * rs[reg], 0.f) & 0xffff);
.LBB0_278:
	s_lshl_b32 s4, s23, 7
	s_waitcnt vmcnt(11)
	v_lshl_add_u32 v130, v188, 6, s4
	s_waitcnt vmcnt(10)
	v_lshl_or_b32 v136, v186, 2, v130
	v_or_b32_e32 v132, 1, v136
	v_ashrrev_i32_e32 v133, 31, v132
	v_lshl_or_b32 v189, s15, 1, v181
	v_lshlrev_b32_e32 v130, 1, v0
	v_mov_b32_e32 v131, v1
	v_lshlrev_b64 v[132:133], 3, v[132:133]
	v_lshl_add_u64 v[134:135], s[24:25], 0, v[130:131]
	s_waitcnt vmcnt(9)
	v_or_b32_e32 v138, 2, v136
	s_movk_i32 s6, 0xc0
	v_or_b32_e32 v132, v132, v189
	v_ashrrev_i32_e32 v139, 31, v138
	v_mad_u64_u32 v[184:185], s[4:5], v132, s6, v[134:135]
	v_mad_i32_i24 v185, v133, s6, v185
	v_lshlrev_b64 v[132:133], 3, v[138:139]
	v_or_b32_e32 v140, 3, v136
	v_or_b32_e32 v132, v132, v189
	v_ashrrev_i32_e32 v141, 31, v140
	s_waitcnt vmcnt(0)
	v_ashrrev_i32_e32 v203, 31, v136
	v_mov_b32_e32 v202, v136
	v_lshl_add_u64 v[202:203], v[202:203], 2, s[20:21]
	global_load_dwordx4 v[204:207], v[202:203], off
	global_load_dwordx4 v[208:211], v[202:203], off offset:32
	global_load_dwordx4 v[212:215], v[202:203], off offset:64
	global_load_dwordx4 v[216:219], v[202:203], off offset:96
	global_load_dwordx4 v[224:227], v[202:203], off offset:128
	global_load_dwordx4 v[234:237], v[202:203], off offset:160
	global_load_dwordx4 v[238:241], v[202:203], off offset:192
	global_load_dwordx4 v[242:245], v[202:203], off offset:224
	v_mad_u64_u32 v[174:175], s[4:5], v132, s6, v[134:135]
	v_mad_i32_i24 v175, v133, s6, v175
	v_lshlrev_b64 v[132:133], 3, v[140:141]
	v_or_b32_e32 v142, 8, v136
	v_or_b32_e32 v132, v132, v189
	v_ashrrev_i32_e32 v143, 31, v142
	v_mad_u64_u32 v[176:177], s[4:5], v132, s6, v[134:135]
	v_mad_i32_i24 v177, v133, s6, v177
	v_lshlrev_b64 v[132:133], 3, v[142:143]
	v_or_b32_e32 v144, 9, v136
	v_or_b32_e32 v132, v132, v189
	v_ashrrev_i32_e32 v145, 31, v144
	v_mad_u64_u32 v[170:171], s[4:5], v132, s6, v[134:135]
	v_mad_i32_i24 v171, v133, s6, v171
	v_lshlrev_b64 v[132:133], 3, v[144:145]
	v_or_b32_e32 v146, 10, v136
	v_or_b32_e32 v132, v132, v189
	v_ashrrev_i32_e32 v147, 31, v146
	v_mad_u64_u32 v[172:173], s[4:5], v132, s6, v[134:135]
	v_mad_i32_i24 v173, v133, s6, v173
	v_lshlrev_b64 v[132:133], 3, v[146:147]
	v_or_b32_e32 v148, 11, v136
	v_or_b32_e32 v132, v132, v189
	v_ashrrev_i32_e32 v149, 31, v148
	v_mad_u64_u32 v[166:167], s[4:5], v132, s6, v[134:135]
	v_mad_i32_i24 v167, v133, s6, v167
	v_lshlrev_b64 v[132:133], 3, v[148:149]
	v_ashrrev_i32_e32 v137, 31, v136
	v_or_b32_e32 v150, 16, v136
	v_or_b32_e32 v132, v132, v189
	v_ashrrev_i32_e32 v151, 31, v150
	v_lshlrev_b64 v[160:161], 3, v[136:137]
	v_mad_u64_u32 v[168:169], s[4:5], v132, s6, v[134:135]
	v_or_b32_e32 v160, v160, v189
	v_mad_i32_i24 v169, v133, s6, v169
	v_lshlrev_b64 v[132:133], 3, v[150:151]
	v_or_b32_e32 v156, 17, v136
	v_mad_u64_u32 v[182:183], s[4:5], v160, s6, v[134:135]
	v_or_b32_e32 v132, v132, v189
	v_ashrrev_i32_e32 v157, 31, v156
	v_mad_i32_i24 v183, v161, s6, v183
	v_mad_u64_u32 v[160:161], s[4:5], v132, s6, v[134:135]
	v_mad_i32_i24 v161, v133, s6, v161
	v_lshlrev_b64 v[132:133], 3, v[156:157]
	v_or_b32_e32 v158, 18, v136
	v_or_b32_e32 v132, v132, v189
	v_ashrrev_i32_e32 v159, 31, v158
	v_mad_u64_u32 v[162:163], s[4:5], v132, s6, v[134:135]
	v_mad_i32_i24 v163, v133, s6, v163
	v_lshlrev_b64 v[132:133], 3, v[158:159]
	v_or_b32_e32 v190, 19, v136
	v_or_b32_e32 v132, v132, v189
	v_ashrrev_i32_e32 v191, 31, v190
	v_mad_u64_u32 v[156:157], s[4:5], v132, s6, v[134:135]
	v_mad_i32_i24 v157, v133, s6, v157
	v_lshlrev_b64 v[132:133], 3, v[190:191]
	v_or_b32_e32 v192, 24, v136
	v_or_b32_e32 v132, v132, v189
	v_ashrrev_i32_e32 v193, 31, v192
	v_mad_u64_u32 v[158:159], s[4:5], v132, s6, v[134:135]
	v_mad_i32_i24 v159, v133, s6, v159
	v_lshlrev_b64 v[132:133], 3, v[192:193]
	v_or_b32_e32 v194, 25, v136
	v_or_b32_e32 v132, v132, v189
	v_ashrrev_i32_e32 v195, 31, v194
	v_mad_u64_u32 v[148:149], s[4:5], v132, s6, v[134:135]
	v_mad_i32_i24 v149, v133, s6, v149
	v_lshlrev_b64 v[132:133], 3, v[194:195]
	v_or_b32_e32 v196, 26, v136
	v_or_b32_e32 v132, v132, v189
	v_lshl_add_u64 v[154:155], v[150:151], 2, s[20:21]
	v_ashrrev_i32_e32 v197, 31, v196
	v_mad_u64_u32 v[150:151], s[4:5], v132, s6, v[134:135]
	v_mad_i32_i24 v151, v133, s6, v151
	v_lshlrev_b64 v[132:133], 3, v[196:197]
	v_or_b32_e32 v198, 27, v136
	v_or_b32_e32 v132, v132, v189
	v_ashrrev_i32_e32 v199, 31, v198
	v_mad_u64_u32 v[144:145], s[4:5], v132, s6, v[134:135]
	v_mad_i32_i24 v145, v133, s6, v145
	v_lshlrev_b64 v[132:133], 3, v[198:199]
	v_or_b32_e32 v132, v132, v189
	v_lshl_add_u64 v[130:131], v[136:137], 2, s[20:21]
	v_mad_u64_u32 v[146:147], s[4:5], v132, s6, v[134:135]
	v_mad_i32_i24 v147, v133, s6, v147
	v_lshl_add_u64 v[164:165], v[142:143], 2, s[20:21]
	v_lshl_add_u64 v[152:153], v[192:193], 2, s[20:21]
	v_lshl_or_b32 v200, v189, 6, v0
	v_lshl_add_u64 v[140:141], v[136:137], 1, s[26:27]
	v_lshlrev_b32_e32 v138, 15, v200
	v_mov_b32_e32 v139, v1
	v_lshl_add_u64 v[142:143], v[140:141], 0, v[138:139]
	s_waitcnt vmcnt(7)
	v_mul_f32_e32 v98, v98, v204
	v_cvt_pk_bf16_f32 v98, v98, s0
	global_store_short v[182:183], v98, off offset:64
	v_mul_f32_e32 v98, v99, v205
	v_cvt_pk_bf16_f32 v98, v98, s0
	v_pk_mul_f32 v[82:83], v[82:83], v[204:205]
	global_store_short v[184:185], v98, off offset:64
	v_cvt_pk_bf16_f32 v98, v82, v83
	v_mul_f32_e32 v82, v116, v206
	v_cvt_pk_bf16_f32 v82, v82, s0
	global_store_short v[174:175], v82, off
	v_mul_f32_e32 v82, v117, v207
	v_cvt_pk_bf16_f32 v82, v82, s0
	global_store_short v[176:177], v82, off
	v_mul_f32_e32 v82, v100, v206
	v_cvt_pk_bf16_f32 v82, v82, s0
	global_store_short v[174:175], v82, off offset:64
	v_mul_f32_e32 v82, v101, v207
	v_cvt_pk_bf16_f32 v82, v82, s0
	global_store_short v[176:177], v82, off offset:64
	v_pk_mul_f32 v[82:83], v[84:85], v[206:207]
	v_mul_f32_e32 v114, v114, v204
	v_cvt_pk_bf16_f32 v99, v82, v83
	v_cvt_pk_bf16_f32 v114, v114, s0
	global_store_short v[182:183], v114, off
	v_mul_f32_e32 v114, v115, v205
	v_cvt_pk_bf16_f32 v114, v114, s0
	global_store_short v[184:185], v114, off
	v_pk_mul_f32 v[66:67], v[66:67], v[204:205]
	v_pk_mul_f32 v[68:69], v[68:69], v[206:207]
	v_cvt_pk_bf16_f32 v66, v66, v67
	v_cvt_pk_bf16_f32 v67, v68, v69
	v_or_b32_e32 v114, 50, v136
	v_ashrrev_i32_e32 v115, 31, v114
	v_or_b32_e32 v116, 51, v136
	v_ashrrev_i32_e32 v117, 31, v116
	s_waitcnt vmcnt(14)
; __device__ __forceinline__ uint32_t pk2(float lo, float hi) { typedef float f2 __attribute__((ext_vector_type(2))); const f2 v = {lo, hi}; return __builtin_bit_cast(uint32_t, __builtin_convertvector(v, bf16x2_t)); }
; __device__ __forceinline__ void mla_up_tile(const Params& p, int b, int it, unsigned char* lds) {
;     ...
; #pragma unroll
;             for (int ni = 0; ni < 2; ++ni) {
; #pragma unroll
;                 for (int reg = 0; reg < 16; ++reg)
;                     KM[((size_t)(mb + (reg & 3) + 8 * (reg >> 2)) * 8 + head) * 96 + ni * 32 + r] = (bf16_t)(pk2(acc[mi][ni][reg] * rs[reg], 0.f) & 0xffff);
;             }
; #pragma unroll
;             for (int ni = 2; ni < 4; ++ni) {
; #pragma unroll
;                 for (int g = 0; g < 4; ++g) {
;                     u32x2 w = {pk2(acc[mi][ni][4 * g] * rs[4 * g], acc[mi][ni][4 * g + 1] * rs[4 * g + 1]), pk2(acc[mi][ni][4 * g + 2] * rs[4 * g + 2], acc[mi][ni][4 * g + 3] * rs[4 * g + 3])};
;                     *(u32x2*)(VTM + (size_t)(head * 64 + (ni - 2) * 32 + r) * TH + mb + 8 * g) = w;
;                 }
	v_mul_f32_e32 v100, v118, v208
	v_cvt_pk_bf16_f32 v100, v100, s0
	global_store_short v[170:171], v100, off
	v_mul_f32_e32 v100, v119, v209
	v_cvt_pk_bf16_f32 v100, v100, s0
	global_store_short v[172:173], v100, off
	v_mul_f32_e32 v100, v102, v208
	v_cvt_pk_bf16_f32 v100, v100, s0
	global_store_short v[170:171], v100, off offset:64
	v_mul_f32_e32 v100, v103, v209
	v_cvt_pk_bf16_f32 v100, v100, s0
	v_pk_mul_f32 v[86:87], v[86:87], v[208:209]
	global_store_short v[172:173], v100, off offset:64
	v_cvt_pk_bf16_f32 v100, v86, v87
	v_mul_f32_e32 v86, v120, v210
	v_cvt_pk_bf16_f32 v86, v86, s0
	global_store_short v[166:167], v86, off
	v_mul_f32_e32 v86, v121, v211
	v_cvt_pk_bf16_f32 v86, v86, s0
	global_store_short v[168:169], v86, off
	v_mul_f32_e32 v86, v104, v210
	v_cvt_pk_bf16_f32 v86, v86, s0
	global_store_short v[166:167], v86, off offset:64
	v_mul_f32_e32 v86, v105, v211
	v_cvt_pk_bf16_f32 v86, v86, s0
	global_store_short v[168:169], v86, off offset:64
	v_pk_mul_f32 v[86:87], v[88:89], v[210:211]
	v_pk_mul_f32 v[68:69], v[72:73], v[210:211]
	v_cvt_pk_bf16_f32 v101, v86, v87
	v_or_b32_e32 v72, 34, v136
	v_ashrrev_i32_e32 v73, 31, v72
	v_or_b32_e32 v118, 56, v136
	v_ashrrev_i32_e32 v119, 31, v118
	v_or_b32_e32 v120, 57, v136
	v_ashrrev_i32_e32 v121, 31, v120
	s_waitcnt vmcnt(21)
	v_mul_f32_e32 v102, v122, v212
	v_cvt_pk_bf16_f32 v102, v102, s0
	global_store_short v[160:161], v102, off
	v_mul_f32_e32 v102, v123, v213
	v_cvt_pk_bf16_f32 v102, v102, s0
	global_store_short v[162:163], v102, off
	v_mul_f32_e32 v102, v106, v212
	v_cvt_pk_bf16_f32 v102, v102, s0
	global_store_short v[160:161], v102, off offset:64
	v_mul_f32_e32 v102, v107, v213
	v_cvt_pk_bf16_f32 v102, v102, s0
	v_pk_mul_f32 v[90:91], v[90:91], v[212:213]
	global_store_short v[162:163], v102, off offset:64
	v_cvt_pk_bf16_f32 v102, v90, v91
	v_mul_f32_e32 v90, v124, v214
	v_cvt_pk_bf16_f32 v90, v90, s0
	global_store_short v[156:157], v90, off
	v_mul_f32_e32 v90, v125, v215
	v_cvt_pk_bf16_f32 v90, v90, s0
	global_store_short v[158:159], v90, off
	v_mul_f32_e32 v90, v108, v214
	v_cvt_pk_bf16_f32 v90, v90, s0
	global_store_short v[156:157], v90, off offset:64
	v_mul_f32_e32 v90, v109, v215
	v_cvt_pk_bf16_f32 v90, v90, s0
	global_store_short v[158:159], v90, off offset:64
	v_pk_mul_f32 v[90:91], v[92:93], v[214:215]
	v_or_b32_e32 v122, 58, v136
	v_cvt_pk_bf16_f32 v103, v90, v91
	v_ashrrev_i32_e32 v123, 31, v122
	v_or_b32_e32 v124, 59, v136
	v_ashrrev_i32_e32 v125, 31, v124
	s_waitcnt vmcnt(28)
	v_pk_mul_f32 v[94:95], v[94:95], v[216:217]
	v_mul_f32_e32 v104, v126, v216
	v_cvt_pk_bf16_f32 v94, v94, v95
	v_mul_f32_e32 v95, v128, v218
	v_cvt_pk_bf16_f32 v104, v104, s0
	v_cvt_pk_bf16_f32 v95, v95, s0
	global_store_short v[148:149], v104, off
	v_mul_f32_e32 v104, v127, v217
	global_store_short v[144:145], v95, off
	v_mul_f32_e32 v95, v129, v219
	v_cvt_pk_bf16_f32 v104, v104, s0
	v_cvt_pk_bf16_f32 v95, v95, s0
	global_store_short v[150:151], v104, off
	v_mul_f32_e32 v104, v110, v216
	global_store_short v[146:147], v95, off
	v_mul_f32_e32 v95, v112, v218
	v_cvt_pk_bf16_f32 v104, v104, s0
	v_cvt_pk_bf16_f32 v95, v95, s0
	global_store_short v[148:149], v104, off offset:64
	v_mul_f32_e32 v104, v111, v217
	global_store_short v[144:145], v95, off offset:64
	v_mul_f32_e32 v95, v113, v219
	v_cvt_pk_bf16_f32 v104, v104, s0
	v_cvt_pk_bf16_f32 v95, v95, s0
	v_pk_mul_f32 v[96:97], v[96:97], v[218:219]
	global_store_short v[150:151], v104, off offset:64
	global_store_short v[146:147], v95, off offset:64
	global_store_dwordx2 v[142:143], v[98:99], off
	global_store_dwordx2 v[142:143], v[100:101], off offset:16
	global_store_dwordx2 v[142:143], v[102:103], off offset:32
	v_cvt_pk_bf16_f32 v95, v96, v97
	global_store_dwordx2 v[142:143], v[94:95], off offset:48
	v_or_b32_e32 v94, 0x100000, v138
	v_mov_b32_e32 v95, v1
	v_lshl_add_u64 v[96:97], v[140:141], 0, v[94:95]
	global_store_dwordx2 v[96:97], v[66:67], off
	v_pk_mul_f32 v[66:67], v[70:71], v[208:209]
	v_or_b32_e32 v70, 33, v136
	v_ashrrev_i32_e32 v71, 31, v70
	v_lshlrev_b64 v[70:71], 3, v[70:71]
	v_or_b32_e32 v70, v70, v189
	v_mad_u64_u32 v[112:113], s[4:5], v70, s6, v[134:135]
	v_cvt_pk_bf16_f32 v66, v66, v67
	v_cvt_pk_bf16_f32 v67, v68, v69
	v_mad_i32_i24 v113, v71, s6, v113
	v_lshlrev_b64 v[70:71], 3, v[72:73]
	global_store_dwordx2 v[96:97], v[66:67], off offset:16
	v_pk_mul_f32 v[66:67], v[74:75], v[212:213]
	v_or_b32_e32 v74, 35, v136
	v_or_b32_e32 v70, v70, v189
	v_ashrrev_i32_e32 v75, 31, v74
	v_mad_u64_u32 v[106:107], s[4:5], v70, s6, v[134:135]
	v_mad_i32_i24 v107, v71, s6, v107
	v_lshlrev_b64 v[70:71], 3, v[74:75]
	v_pk_mul_f32 v[68:69], v[76:77], v[214:215]
	v_or_b32_e32 v76, 40, v136
	v_or_b32_e32 v70, v70, v189
	v_ashrrev_i32_e32 v77, 31, v76
	v_mad_u64_u32 v[108:109], s[4:5], v70, s6, v[134:135]
	v_cvt_pk_bf16_f32 v66, v66, v67
	v_cvt_pk_bf16_f32 v67, v68, v69
	v_mad_i32_i24 v109, v71, s6, v109
	v_lshlrev_b64 v[70:71], 3, v[76:77]
	global_store_dwordx2 v[96:97], v[66:67], off offset:32
	v_pk_mul_f32 v[66:67], v[78:79], v[216:217]
	v_or_b32_e32 v78, 41, v136
	v_or_b32_e32 v70, v70, v189
	v_ashrrev_i32_e32 v79, 31, v78
	v_mad_u64_u32 v[102:103], s[4:5], v70, s6, v[134:135]
	v_mad_i32_i24 v103, v71, s6, v103
	v_lshlrev_b64 v[70:71], 3, v[78:79]
	v_pk_mul_f32 v[68:69], v[80:81], v[218:219]
	v_or_b32_e32 v80, 42, v136
	v_or_b32_e32 v70, v70, v189
	v_ashrrev_i32_e32 v81, 31, v80
	v_mad_u64_u32 v[104:105], s[4:5], v70, s6, v[134:135]
	v_mad_i32_i24 v105, v71, s6, v105
	v_lshlrev_b64 v[70:71], 3, v[80:81]
	v_or_b32_e32 v86, 43, v136
	v_or_b32_e32 v70, v70, v189
	v_ashrrev_i32_e32 v87, 31, v86
	v_mad_u64_u32 v[98:99], s[4:5], v70, s6, v[134:135]
; __device__ __forceinline__ uint32_t pk2(float lo, float hi) { typedef float f2 __attribute__((ext_vector_type(2))); const f2 v = {lo, hi}; return __builtin_bit_cast(uint32_t, __builtin_convertvector(v, bf16x2_t)); }
; __device__ __forceinline__ void mla_up_tile(const Params& p, int b, int it, unsigned char* lds) {
;     ...
;         for (int mi = 0; mi < 2; ++mi) {
;             const int mb = pm * 128 + wr * 64 + mi * 32 + 4 * h;
;             float rs[16];
; #pragma unroll
;             for (int reg = 0; reg < 16; ++reg) rs[reg] = RKV[mb + (reg & 3) + 8 * (reg >> 2)];
; #pragma unroll
;             for (int ni = 0; ni < 2; ++ni) {
; #pragma unroll
;                 for (int reg = 0; reg < 16; ++reg)
;                     KM[((size_t)(mb + (reg & 3) + 8 * (reg >> 2)) * 8 + head) * 96 + ni * 32 + r] = (bf16_t)(pk2(acc[mi][ni][reg] * rs[reg], 0.f) & 0xffff);
	v_cvt_pk_bf16_f32 v66, v66, v67
	v_cvt_pk_bf16_f32 v67, v68, v69
	v_or_b32_e32 v68, 32, v136
	v_mad_i32_i24 v99, v71, s6, v99
	v_lshlrev_b64 v[70:71], 3, v[86:87]
	v_ashrrev_i32_e32 v69, 31, v68
	v_or_b32_e32 v88, 48, v136
	v_or_b32_e32 v70, v70, v189
	v_ashrrev_i32_e32 v89, 31, v88
	v_lshlrev_b64 v[90:91], 3, v[68:69]
	v_mad_u64_u32 v[100:101], s[4:5], v70, s6, v[134:135]
	v_or_b32_e32 v90, v90, v189
	v_mad_i32_i24 v101, v71, s6, v101
	v_lshlrev_b64 v[70:71], 3, v[88:89]
	v_or_b32_e32 v92, 49, v136
	v_mad_u64_u32 v[110:111], s[4:5], v90, s6, v[134:135]
	v_or_b32_e32 v70, v70, v189
	v_ashrrev_i32_e32 v93, 31, v92
	v_mad_i32_i24 v111, v91, s6, v111
	v_mad_u64_u32 v[90:91], s[4:5], v70, s6, v[134:135]
	v_mad_i32_i24 v91, v71, s6, v91
	v_lshlrev_b64 v[70:71], 3, v[92:93]
	v_or_b32_e32 v70, v70, v189
	v_mad_u64_u32 v[92:93], s[4:5], v70, s6, v[134:135]
	v_mad_i32_i24 v93, v71, s6, v93
	v_lshlrev_b64 v[70:71], 3, v[114:115]
	v_or_b32_e32 v70, v70, v189
	v_mad_u64_u32 v[86:87], s[4:5], v70, s6, v[134:135]
	v_mad_i32_i24 v87, v71, s6, v87
	v_lshlrev_b64 v[70:71], 3, v[116:117]
	v_or_b32_e32 v70, v70, v189
	v_lshl_add_u64 v[84:85], v[88:89], 2, s[20:21]
	v_mad_u64_u32 v[88:89], s[4:5], v70, s6, v[134:135]
	v_mad_i32_i24 v89, v71, s6, v89
	v_lshlrev_b64 v[70:71], 3, v[118:119]
	v_or_b32_e32 v70, v70, v189
	v_mad_u64_u32 v[78:79], s[4:5], v70, s6, v[134:135]
	v_mad_i32_i24 v79, v71, s6, v79
	v_lshlrev_b64 v[70:71], 3, v[120:121]
	v_or_b32_e32 v70, v70, v189
	v_mad_u64_u32 v[80:81], s[4:5], v70, s6, v[134:135]
	v_mad_i32_i24 v81, v71, s6, v81
	v_lshlrev_b64 v[70:71], 3, v[122:123]
	v_or_b32_e32 v70, v70, v189
	v_mad_u64_u32 v[74:75], s[4:5], v70, s6, v[134:135]
	v_mad_i32_i24 v75, v71, s6, v75
	v_lshlrev_b64 v[70:71], 3, v[124:125]
	v_or_b32_e32 v70, v70, v189
	global_store_dwordx2 v[96:97], v[66:67], off offset:48
	v_lshl_add_u64 v[66:67], v[68:69], 2, s[20:21]
	v_lshl_add_u64 v[96:97], v[76:77], 2, s[20:21]
	v_mad_u64_u32 v[76:77], s[4:5], v70, s6, v[134:135]
	v_mad_i32_i24 v77, v71, s6, v77
	v_lshlrev_b64 v[70:71], 1, v[68:69]
	v_lshl_add_u64 v[82:83], v[118:119], 2, s[20:21]
	v_lshl_add_u64 v[72:73], s[26:27], 0, v[138:139]
	v_lshl_add_u64 v[72:73], v[72:73], 0, v[70:71]
	s_mov_b64 s[4:5], 0
	s_waitcnt vmcnt(43)
	v_mul_f32_e32 v34, v34, v224
	v_cvt_pk_bf16_f32 v34, v34, s0
	global_store_short v[110:111], v34, off offset:64
	v_mul_f32_e32 v34, v35, v225
	v_cvt_pk_bf16_f32 v34, v34, s0
	v_pk_mul_f32 v[18:19], v[18:19], v[224:225]
	global_store_short v[112:113], v34, off offset:64
	v_cvt_pk_bf16_f32 v34, v18, v19
	v_mul_f32_e32 v18, v52, v226
	v_cvt_pk_bf16_f32 v18, v18, s0
	global_store_short v[106:107], v18, off
	v_mul_f32_e32 v18, v53, v227
	v_cvt_pk_bf16_f32 v18, v18, s0
	global_store_short v[108:109], v18, off
	v_mul_f32_e32 v18, v36, v226
	v_cvt_pk_bf16_f32 v18, v18, s0
	global_store_short v[106:107], v18, off offset:64
	v_mul_f32_e32 v18, v37, v227
	v_cvt_pk_bf16_f32 v18, v18, s0
	global_store_short v[108:109], v18, off offset:64
	v_pk_mul_f32 v[18:19], v[20:21], v[226:227]
	v_mul_f32_e32 v50, v50, v224
	v_cvt_pk_bf16_f32 v35, v18, v19
	v_cvt_pk_bf16_f32 v50, v50, s0
	global_store_short v[110:111], v50, off
	v_mul_f32_e32 v50, v51, v225
	v_cvt_pk_bf16_f32 v50, v50, s0
	global_store_short v[112:113], v50, off
	v_pk_mul_f32 v[2:3], v[2:3], v[224:225]
	v_pk_mul_f32 v[4:5], v[4:5], v[226:227]
	v_cvt_pk_bf16_f32 v2, v2, v3
	v_cvt_pk_bf16_f32 v3, v4, v5
	s_waitcnt vmcnt(50)
; __device__ __forceinline__ uint32_t pk2(float lo, float hi) { typedef float f2 __attribute__((ext_vector_type(2))); const f2 v = {lo, hi}; return __builtin_bit_cast(uint32_t, __builtin_convertvector(v, bf16x2_t)); }
; __device__ __forceinline__ void mla_up_tile(const Params& p, int b, int it, unsigned char* lds) {
;     ...
;         for (int mi = 0; mi < 2; ++mi) {
;             const int mb = pm * 128 + wr * 64 + mi * 32 + 4 * h;
;             float rs[16];
; #pragma unroll
;             for (int reg = 0; reg < 16; ++reg) rs[reg] = RKV[mb + (reg & 3) + 8 * (reg >> 2)];
; #pragma unroll
;             for (int ni = 0; ni < 2; ++ni) {
; #pragma unroll
;                 for (int reg = 0; reg < 16; ++reg)
;                     KM[((size_t)(mb + (reg & 3) + 8 * (reg >> 2)) * 8 + head) * 96 + ni * 32 + r] = (bf16_t)(pk2(acc[mi][ni][reg] * rs[reg], 0.f) & 0xffff);
;             }
; #pragma unroll
;             for (int ni = 2; ni < 4; ++ni) {
; #pragma unroll
;                 for (int g = 0; g < 4; ++g) {
;                     u32x2 w = {pk2(acc[mi][ni][4 * g] * rs[4 * g], acc[mi][ni][4 * g + 1] * rs[4 * g + 1]), pk2(acc[mi][ni][4 * g + 2] * rs[4 * g + 2], acc[mi][ni][4 * g + 3] * rs[4 * g + 3])};
;                     *(u32x2*)(VTM + (size_t)(head * 64 + (ni - 2) * 32 + r) * TH + mb + 8 * g) = w;
;                 }
	v_mul_f32_e32 v36, v54, v234
	v_cvt_pk_bf16_f32 v36, v36, s0
	global_store_short v[102:103], v36, off
	v_mul_f32_e32 v36, v55, v235
	v_cvt_pk_bf16_f32 v36, v36, s0
	global_store_short v[104:105], v36, off
	v_mul_f32_e32 v36, v38, v234
	v_cvt_pk_bf16_f32 v36, v36, s0
	global_store_short v[102:103], v36, off offset:64
	v_mul_f32_e32 v36, v39, v235
	v_cvt_pk_bf16_f32 v36, v36, s0
	v_pk_mul_f32 v[22:23], v[22:23], v[234:235]
	global_store_short v[104:105], v36, off offset:64
	v_cvt_pk_bf16_f32 v36, v22, v23
	v_mul_f32_e32 v22, v56, v236
	v_cvt_pk_bf16_f32 v22, v22, s0
	global_store_short v[98:99], v22, off
	v_mul_f32_e32 v22, v57, v237
	v_cvt_pk_bf16_f32 v22, v22, s0
	global_store_short v[100:101], v22, off
	v_mul_f32_e32 v22, v40, v236
	v_cvt_pk_bf16_f32 v22, v22, s0
	global_store_short v[98:99], v22, off offset:64
	v_mul_f32_e32 v22, v41, v237
	v_cvt_pk_bf16_f32 v22, v22, s0
	global_store_short v[100:101], v22, off offset:64
	v_pk_mul_f32 v[22:23], v[24:25], v[236:237]
	v_pk_mul_f32 v[4:5], v[8:9], v[236:237]
	v_cvt_pk_bf16_f32 v37, v22, v23
	s_waitcnt vmcnt(57)
	v_mul_f32_e32 v38, v58, v238
	v_cvt_pk_bf16_f32 v38, v38, s0
	global_store_short v[90:91], v38, off
	v_mul_f32_e32 v38, v59, v239
	v_cvt_pk_bf16_f32 v38, v38, s0
	global_store_short v[92:93], v38, off
	v_mul_f32_e32 v38, v42, v238
	v_cvt_pk_bf16_f32 v38, v38, s0
	global_store_short v[90:91], v38, off offset:64
	v_mul_f32_e32 v38, v43, v239
	v_cvt_pk_bf16_f32 v38, v38, s0
	v_pk_mul_f32 v[26:27], v[26:27], v[238:239]
	global_store_short v[92:93], v38, off offset:64
	v_cvt_pk_bf16_f32 v38, v26, v27
	v_mul_f32_e32 v26, v60, v240
	v_cvt_pk_bf16_f32 v26, v26, s0
	global_store_short v[86:87], v26, off
	v_mul_f32_e32 v26, v61, v241
	v_cvt_pk_bf16_f32 v26, v26, s0
	global_store_short v[88:89], v26, off
	v_mul_f32_e32 v26, v44, v240
	v_cvt_pk_bf16_f32 v26, v26, s0
	global_store_short v[86:87], v26, off offset:64
	v_mul_f32_e32 v26, v45, v241
	v_cvt_pk_bf16_f32 v26, v26, s0
	global_store_short v[88:89], v26, off offset:64
	v_pk_mul_f32 v[26:27], v[28:29], v[240:241]
	s_nop 0
	v_cvt_pk_bf16_f32 v39, v26, v27
	s_waitcnt vmcnt(63)
	v_pk_mul_f32 v[30:31], v[30:31], v[242:243]
	v_mul_f32_e32 v40, v62, v242
	v_cvt_pk_bf16_f32 v30, v30, v31
	v_mul_f32_e32 v31, v64, v244
	v_cvt_pk_bf16_f32 v40, v40, s0
	v_cvt_pk_bf16_f32 v31, v31, s0
	global_store_short v[78:79], v40, off
	v_mul_f32_e32 v40, v63, v243
	global_store_short v[74:75], v31, off
	v_mul_f32_e32 v31, v65, v245
	v_cvt_pk_bf16_f32 v40, v40, s0
	v_cvt_pk_bf16_f32 v31, v31, s0
	global_store_short v[80:81], v40, off
	v_mul_f32_e32 v40, v46, v242
	global_store_short v[76:77], v31, off
	v_mul_f32_e32 v31, v48, v244
	v_cvt_pk_bf16_f32 v40, v40, s0
	v_cvt_pk_bf16_f32 v31, v31, s0
	global_store_short v[78:79], v40, off offset:64
	v_mul_f32_e32 v40, v47, v243
	global_store_short v[74:75], v31, off offset:64
	v_mul_f32_e32 v31, v49, v245
	v_cvt_pk_bf16_f32 v40, v40, s0
	v_cvt_pk_bf16_f32 v31, v31, s0
	v_pk_mul_f32 v[32:33], v[32:33], v[244:245]
	global_store_short v[80:81], v40, off offset:64
	global_store_short v[76:77], v31, off offset:64
	global_store_dwordx2 v[72:73], v[34:35], off
	global_store_dwordx2 v[72:73], v[36:37], off offset:16
	global_store_dwordx2 v[72:73], v[38:39], off offset:32
	v_cvt_pk_bf16_f32 v31, v32, v33
	global_store_dwordx2 v[72:73], v[30:31], off offset:48
	v_lshl_add_u64 v[30:31], s[26:27], 0, v[94:95]
	v_lshl_add_u64 v[30:31], v[30:31], 0, v[70:71]
	global_store_dwordx2 v[30:31], v[2:3], off
	v_pk_mul_f32 v[2:3], v[6:7], v[234:235]
	s_nop 0
	v_cvt_pk_bf16_f32 v2, v2, v3
	v_cvt_pk_bf16_f32 v3, v4, v5
	global_store_dwordx2 v[30:31], v[2:3], off offset:16
	v_pk_mul_f32 v[2:3], v[10:11], v[238:239]
	v_pk_mul_f32 v[4:5], v[12:13], v[240:241]
	v_cvt_pk_bf16_f32 v2, v2, v3
	v_cvt_pk_bf16_f32 v3, v4, v5
	global_store_dwordx2 v[30:31], v[2:3], off offset:32
	v_pk_mul_f32 v[2:3], v[14:15], v[242:243]
	v_pk_mul_f32 v[4:5], v[16:17], v[244:245]
	v_cvt_pk_bf16_f32 v2, v2, v3
	v_cvt_pk_bf16_f32 v3, v4, v5
	global_store_dwordx2 v[30:31], v[2:3], off offset:48
